# prompt attention: waves 4-7 start each tile loop 640 cycles late (stagger)
# baseline (speedup 1.0000x reference)
.LBB0_81:
	s_cmp_lt_i32 s31, s26
	s_cselect_b64 s[0:1], -1, 0
	s_cmp_gt_i32 s31, s22
	s_cselect_b64 s[12:13], -1, 0
	s_or_b64 s[0:1], s[0:1], s[12:13]
	s_and_b64 vcc, exec, s[0:1]
	s_cbranch_vccnz .LBB0_88
	s_lshl_b32 s0, s31, 6
	v_sub_u32_e32 v183, s0, v155
	s_mov_b32 s33, 0
	s_cmp_lt_u32 s62, 4
	s_cbranch_scc1 .Lpa0_nodelay
	s_sleep 10
.Lpa0_nodelay:
.Lpa0_tile:
	v_or_b32_e32 v66, s33, v149
	v_mad_u32_u24 v188, v66, s97, v176
	ds_read_b128 v[206:209], v188
	ds_read_b128 v[210:213], v188 offset:32
	ds_read_b128 v[214:217], v188 offset:64
	ds_read_b128 v[224:227], v188 offset:96
	ds_read_b128 v[232:235], v188 offset:128
	ds_read_b128 v[236:239], v188 offset:160
	ds_read_b128 v[240:243], v188 offset:192
	ds_read_b128 v[184:187], v188 offset:224
	v_add_u32_e32 v190, s33, v183
	v_lshl_add_u32 v197, s33, 1, v180
	v_cmp_gt_i32_e64 s[12:13], s61, v190
	v_cmp_lt_i32_e64 s[0:1], s64, v190
	v_add_u32_e32 v198, 0x4400, v197
	v_add_u32_e32 v201, 0x5600, v197
	v_add_u32_e32 v203, 0x6800, v197
	v_add_u32_e32 v197, 0x7a00, v197
	s_waitcnt lgkmcnt(7)
	v_mfma_f32_32x32x16_bf16 v[66:81], v[206:209], v[102:105], 0
	s_waitcnt lgkmcnt(6)
	v_mfma_f32_32x32x16_bf16 v[66:81], v[210:213], v[106:109], v[66:81]
	s_waitcnt lgkmcnt(5)
	v_mfma_f32_32x32x16_bf16 v[66:81], v[214:217], v[114:117], v[66:81]
	s_waitcnt lgkmcnt(4)
	v_mfma_f32_32x32x16_bf16 v[66:81], v[224:227], v[118:121], v[66:81]
	s_waitcnt lgkmcnt(3)
	v_mfma_f32_32x32x16_bf16 v[66:81], v[232:235], v[122:125], v[66:81]
	s_waitcnt lgkmcnt(2)
	v_mfma_f32_32x32x16_bf16 v[66:81], v[236:239], v[126:129], v[66:81]
	s_waitcnt lgkmcnt(1)
	v_mfma_f32_32x32x16_bf16 v[66:81], v[240:243], v[130:133], v[66:81]
	s_waitcnt lgkmcnt(0)
	v_mfma_f32_32x32x16_bf16 v[66:81], v[184:187], v[134:137], v[66:81]
	s_and_saveexec_b64 s[14:15], s[0:1]
	s_cbranch_execz .Lpa0_nobias
	v_add_u32_e32 v190, v190, v148
	v_med3_i32 v188, v190, s39, 63
	v_lshl_add_u32 v188, v188, 2, s66
	v_add_u32_e32 v192, 1, v190
	v_med3_i32 v192, v192, s39, 63
	v_lshl_add_u32 v192, v192, 2, s66
	v_add_u32_e32 v193, 2, v190
	v_med3_i32 v193, v193, s39, 63
	v_lshl_add_u32 v193, v193, 2, s66
	v_add_u32_e32 v194, 3, v190
	v_med3_i32 v194, v194, s39, 63
	v_lshl_add_u32 v194, v194, 2, s66
	v_add_u32_e32 v195, 8, v190
	v_med3_i32 v195, v195, s39, 63
	v_lshl_add_u32 v195, v195, 2, s66
	v_add_u32_e32 v196, 9, v190
	v_med3_i32 v196, v196, s39, 63
	v_lshl_add_u32 v196, v196, 2, s66
	v_add_u32_e32 v199, 10, v190
	v_med3_i32 v199, v199, s39, 63
	v_lshl_add_u32 v199, v199, 2, s66
	v_add_u32_e32 v200, 11, v190
	v_med3_i32 v200, v200, s39, 63
	v_lshl_add_u32 v200, v200, 2, s66
	v_add_u32_e32 v202, 16, v190
	v_med3_i32 v202, v202, s39, 63
	v_lshl_add_u32 v202, v202, 2, s66
	v_add_u32_e32 v204, 17, v190
	v_med3_i32 v204, v204, s39, 63
	v_lshl_add_u32 v204, v204, 2, s66
	v_add_u32_e32 v205, 18, v190
	v_med3_i32 v205, v205, s39, 63
	v_lshl_add_u32 v205, v205, 2, s66
	v_add_u32_e32 v218, 19, v190
	v_med3_i32 v218, v218, s39, 63
	v_lshl_add_u32 v218, v218, 2, s66
	v_add_u32_e32 v219, 24, v190
	v_med3_i32 v219, v219, s39, 63
	v_lshl_add_u32 v219, v219, 2, s66
	v_add_u32_e32 v223, 25, v190
	v_med3_i32 v223, v223, s39, 63
	v_lshl_add_u32 v223, v223, 2, s66
	v_add_u32_e32 v244, 26, v190
	v_med3_i32 v244, v244, s39, 63
	v_lshl_add_u32 v244, v244, 2, s66
	v_add_u32_e32 v190, 27, v190
	v_med3_i32 v190, v190, s39, 63
	v_lshl_add_u32 v190, v190, 2, s66
	ds_read_b32 v188, v188 offset:512
	ds_read_b32 v192, v192 offset:512
	ds_read_b32 v193, v193 offset:512
	ds_read_b32 v194, v194 offset:512
	ds_read_b32 v195, v195 offset:512
	ds_read_b32 v196, v196 offset:512
	ds_read_b32 v199, v199 offset:512
	ds_read_b32 v200, v200 offset:512
	ds_read_b32 v202, v202 offset:512
	ds_read_b32 v204, v204 offset:512
	ds_read_b32 v205, v205 offset:512
	ds_read_b32 v218, v218 offset:512
	ds_read_b32 v219, v219 offset:512
	ds_read_b32 v223, v223 offset:512
	ds_read_b32 v244, v244 offset:512
	ds_read_b32 v190, v190 offset:512
	s_mov_b64 exec, s[14:15]
	ds_read2_b64 v[206:209], v198 offset1:2
	ds_read2_b64 v[210:213], v201 offset1:2
	ds_read2_b64 v[214:217], v203 offset1:2
	ds_read2_b64 v[224:227], v197 offset1:2
	ds_read2_b64 v[232:235], v198 offset0:4 offset1:6
	ds_read2_b64 v[236:239], v201 offset0:4 offset1:6
	ds_read2_b64 v[240:243], v203 offset0:4 offset1:6
	ds_read2_b64 v[184:187], v197 offset0:4 offset1:6
	s_waitcnt lgkmcnt(8)
	s_and_b64 exec, s[14:15], s[0:1]
	v_add_f32_e32 v66, v66, v188
	v_add_f32_e32 v67, v67, v192
	v_add_f32_e32 v68, v68, v193
	v_add_f32_e32 v69, v69, v194
	v_add_f32_e32 v70, v70, v195
	v_add_f32_e32 v71, v71, v196
	v_add_f32_e32 v72, v72, v199
	v_add_f32_e32 v73, v73, v200
	v_add_f32_e32 v74, v74, v202
	v_add_f32_e32 v75, v75, v204
	v_add_f32_e32 v76, v76, v205
	v_add_f32_e32 v77, v77, v218
	v_add_f32_e32 v78, v78, v219
	v_add_f32_e32 v79, v79, v223
	v_add_f32_e32 v80, v80, v244
	v_add_f32_e32 v81, v81, v190
	s_mov_b64 exec, s[14:15]
	s_branch .Lpa0_max

.LBB0_90:
	s_or_b32 s0, s31, 1
	s_cmp_lt_i32 s0, s26
	s_cselect_b64 s[12:13], -1, 0
	s_cmp_ge_i32 s31, s22
	s_cselect_b64 s[14:15], -1, 0
	s_or_b64 s[12:13], s[14:15], s[12:13]
	s_and_b64 vcc, exec, s[12:13]
	s_cbranch_vccnz .LBB0_97
	s_lshl_b32 s0, s0, 6
	v_sub_u32_e32 v183, s0, v155
	s_mov_b32 s33, 0
	s_cmp_lt_u32 s62, 4
	s_cbranch_scc1 .Lpa1_nodelay
	s_sleep 10
.Lpa1_nodelay:
.Lpa1_tile:
	v_or_b32_e32 v66, s33, v149
	v_mad_u32_u24 v188, v66, s97, v176
	ds_read_b128 v[206:209], v188 offset:35840
	ds_read_b128 v[210:213], v188 offset:35872
	ds_read_b128 v[214:217], v188 offset:35904
	ds_read_b128 v[224:227], v188 offset:35936
	ds_read_b128 v[232:235], v188 offset:35968
	ds_read_b128 v[236:239], v188 offset:36000
	ds_read_b128 v[240:243], v188 offset:36032
	ds_read_b128 v[184:187], v188 offset:36064
	v_add_u32_e32 v190, s33, v183
	v_lshl_add_u32 v197, s33, 1, v180
	v_cmp_gt_i32_e64 s[12:13], s61, v190
	v_cmp_lt_i32_e64 s[0:1], s64, v190
	v_add_u32_e32 v198, 0xd000, v197
	v_add_u32_e32 v201, 0xe200, v197
	v_add_u32_e32 v203, 0xf400, v197
	v_add_u32_e32 v197, 0x10600, v197
	s_waitcnt lgkmcnt(7)
	v_mfma_f32_32x32x16_bf16 v[66:81], v[206:209], v[102:105], 0
	s_waitcnt lgkmcnt(6)
	v_mfma_f32_32x32x16_bf16 v[66:81], v[210:213], v[106:109], v[66:81]
	s_waitcnt lgkmcnt(5)
	v_mfma_f32_32x32x16_bf16 v[66:81], v[214:217], v[114:117], v[66:81]
	s_waitcnt lgkmcnt(4)
	v_mfma_f32_32x32x16_bf16 v[66:81], v[224:227], v[118:121], v[66:81]
	s_waitcnt lgkmcnt(3)
	v_mfma_f32_32x32x16_bf16 v[66:81], v[232:235], v[122:125], v[66:81]
	s_waitcnt lgkmcnt(2)
	v_mfma_f32_32x32x16_bf16 v[66:81], v[236:239], v[126:129], v[66:81]
	s_waitcnt lgkmcnt(1)
	v_mfma_f32_32x32x16_bf16 v[66:81], v[240:243], v[130:133], v[66:81]
	s_waitcnt lgkmcnt(0)
	v_mfma_f32_32x32x16_bf16 v[66:81], v[184:187], v[134:137], v[66:81]
	s_and_saveexec_b64 s[14:15], s[0:1]
	s_cbranch_execz .Lpa1_nobias
	v_add_u32_e32 v190, v190, v148
	v_med3_i32 v188, v190, s39, 63
	v_lshl_add_u32 v188, v188, 2, s66
	v_add_u32_e32 v192, 1, v190
	v_med3_i32 v192, v192, s39, 63
	v_lshl_add_u32 v192, v192, 2, s66
	v_add_u32_e32 v193, 2, v190
	v_med3_i32 v193, v193, s39, 63
	v_lshl_add_u32 v193, v193, 2, s66
	v_add_u32_e32 v194, 3, v190
	v_med3_i32 v194, v194, s39, 63
	v_lshl_add_u32 v194, v194, 2, s66
	v_add_u32_e32 v195, 8, v190
	v_med3_i32 v195, v195, s39, 63
	v_lshl_add_u32 v195, v195, 2, s66
	v_add_u32_e32 v196, 9, v190
	v_med3_i32 v196, v196, s39, 63
	v_lshl_add_u32 v196, v196, 2, s66
	v_add_u32_e32 v199, 10, v190
	v_med3_i32 v199, v199, s39, 63
	v_lshl_add_u32 v199, v199, 2, s66
	v_add_u32_e32 v200, 11, v190
	v_med3_i32 v200, v200, s39, 63
	v_lshl_add_u32 v200, v200, 2, s66
	v_add_u32_e32 v202, 16, v190
	v_med3_i32 v202, v202, s39, 63
	v_lshl_add_u32 v202, v202, 2, s66
	v_add_u32_e32 v204, 17, v190
	v_med3_i32 v204, v204, s39, 63
	v_lshl_add_u32 v204, v204, 2, s66
	v_add_u32_e32 v205, 18, v190
	v_med3_i32 v205, v205, s39, 63
	v_lshl_add_u32 v205, v205, 2, s66
	v_add_u32_e32 v218, 19, v190
	v_med3_i32 v218, v218, s39, 63
	v_lshl_add_u32 v218, v218, 2, s66
	v_add_u32_e32 v219, 24, v190
	v_med3_i32 v219, v219, s39, 63
	v_lshl_add_u32 v219, v219, 2, s66
	v_add_u32_e32 v223, 25, v190
	v_med3_i32 v223, v223, s39, 63
	v_lshl_add_u32 v223, v223, 2, s66
	v_add_u32_e32 v244, 26, v190
	v_med3_i32 v244, v244, s39, 63
	v_lshl_add_u32 v244, v244, 2, s66
	v_add_u32_e32 v190, 27, v190
	v_med3_i32 v190, v190, s39, 63
	v_lshl_add_u32 v190, v190, 2, s66
	ds_read_b32 v188, v188 offset:512
	ds_read_b32 v192, v192 offset:512
	ds_read_b32 v193, v193 offset:512
	ds_read_b32 v194, v194 offset:512
	ds_read_b32 v195, v195 offset:512
	ds_read_b32 v196, v196 offset:512
	ds_read_b32 v199, v199 offset:512
	ds_read_b32 v200, v200 offset:512
	ds_read_b32 v202, v202 offset:512
	ds_read_b32 v204, v204 offset:512
	ds_read_b32 v205, v205 offset:512
	ds_read_b32 v218, v218 offset:512
	ds_read_b32 v219, v219 offset:512
	ds_read_b32 v223, v223 offset:512
	ds_read_b32 v244, v244 offset:512
	ds_read_b32 v190, v190 offset:512
	s_mov_b64 exec, s[14:15]
	ds_read2_b64 v[206:209], v198 offset1:2
	ds_read2_b64 v[210:213], v201 offset1:2
	ds_read2_b64 v[214:217], v203 offset1:2
	ds_read2_b64 v[224:227], v197 offset1:2
	ds_read2_b64 v[232:235], v198 offset0:4 offset1:6
	ds_read2_b64 v[236:239], v201 offset0:4 offset1:6
	ds_read2_b64 v[240:243], v203 offset0:4 offset1:6
	ds_read2_b64 v[184:187], v197 offset0:4 offset1:6
	s_waitcnt lgkmcnt(8)
	s_and_b64 exec, s[14:15], s[0:1]
	v_add_f32_e32 v66, v66, v188
	v_add_f32_e32 v67, v67, v192
	v_add_f32_e32 v68, v68, v193
	v_add_f32_e32 v69, v69, v194
	v_add_f32_e32 v70, v70, v195
	v_add_f32_e32 v71, v71, v196
	v_add_f32_e32 v72, v72, v199
	v_add_f32_e32 v73, v73, v200
	v_add_f32_e32 v74, v74, v202
	v_add_f32_e32 v75, v75, v204
	v_add_f32_e32 v76, v76, v205
	v_add_f32_e32 v77, v77, v218
	v_add_f32_e32 v78, v78, v219
	v_add_f32_e32 v79, v79, v223
	v_add_f32_e32 v80, v80, v244
	v_add_f32_e32 v81, v81, v190
	s_mov_b64 exec, s[14:15]
	s_branch .Lpa1_max
